# attention main loop: half-step stagger between waves 0-3 and 4-7 (waves 4-7 take the per-step barrier after the mid-step K/V DMA issue, waves 0-3 issue their DMA right after the end-of-step barrier)
# baseline (speedup 1.0000x reference)
; #define WAIT_BAR(N) asm volatile("s_waitcnt vmcnt(" #N ") lgkmcnt(0)\n\ts_barrier":::"memory")
;   #define DMA_K(t,slot) glds16(ksrc+(long)(t)*KVBLK*DM,(unsigned)__builtin_amdgcn_readfirstlane(kdst+(slot)))
;   #define DMA_V(t,slot) do{ glds16(vsrc+(long)(t)*KVBLK*DM,(unsigned)__builtin_amdgcn_readfirstlane(vdst+2*(slot))); glds16(vsrc+64+(long)(t)*KVBLK*DM,(unsigned)__builtin_amdgcn_readfirstlane(vdst+2*(slot)+8192)); }while(0)
;   #define ROT() do{sl_prev=sl_cur;sl_cur=sl_next;sl_next=(sl_next==(NSLOT-1)*SLOTB)?0:sl_next+SLOTB;}while(0)
; template<int THRL,bool FIXED> __device__ __forceinline__ void attn_unit(int qb,const bf16*Q,const bf16*__restrict__ Kh,const bf16*__restrict__ Vh,bf16*O,const int*__restrict__ cid,char*shm,const int wid){
;     ...
;   _Pragma("unroll") for(int r=0;r<16;++r)pA1[r]=__builtin_amdgcn_exp2f(pA1[r]);
;   WAIT_BAR(0);
;   DMA_K(3,0);DMA_V(1,SLOTB);
;   ROT();
;   kload8(kf,kp0+sl_cur);
;   WAIT_BAR(3);
;   s16x4 vlo[8],vhi[8]; u32x4 pw0,pw1,pw2,pw3;
.LBB0_1060:
	s_waitcnt vmcnt(0) lgkmcnt(0)
	s_barrier
	s_nop 10
	v_exp_f32_e32 v82, v2
	v_exp_f32_e32 v83, v3
	v_lshl_add_u64 v[2:3], v[34:35], 0, s[66:67]
	s_mov_b32 s0, m0
	s_mov_b32 m0, s96
	s_nop 0
	global_load_lds_dwordx4 v[2:3], off
	s_mov_b32 m0, s0
	s_cmp_lg_u32 0, -1
	s_cselect_b32 s0, 0, 0
	s_add_i32 s0, s0, s3
	v_lshl_add_u64 v[2:3], v[36:37], 0, s[14:15]
	s_add_i32 s1, s0, 0xa000
	s_mov_b32 s4, m0
	s_mov_b32 m0, s1
	s_nop 0
	global_load_lds_dwordx4 v[2:3], off
	s_mov_b32 m0, s4
	v_lshl_add_u64 v[2:3], v[36:37], 0, s[74:75]
	s_add_i32 s0, s0, 0xc000
	s_mov_b32 s1, m0
	s_mov_b32 m0, s0
	s_nop 0
	global_load_lds_dwordx4 v[2:3], off
	s_mov_b32 m0, s1
	ds_read_b128 v[206:209], v238 offset:8192
	ds_read_b128 v[202:205], v238 offset:8704
	ds_read_b128 v[198:201], v238 offset:10240
	ds_read_b128 v[194:197], v238 offset:10752
	ds_read_b128 v[190:193], v238 offset:12288
	ds_read_b128 v[186:189], v238 offset:12800
	ds_read_b128 v[182:185], v238 offset:14336
	ds_read_b128 v[178:181], v238 offset:14848
	v_lshlrev_b32_e32 v0, 1, v222
	v_and_b32_e32 v239, 32, v0
	v_lshlrev_b32_e32 v0, 4, v222
	v_and_b32_e32 v0, 0xc0, v0
	v_exp_f32_e32 v98, v18
	v_exp_f32_e32 v99, v19
	v_exp_f32_e32 v100, v20
	v_exp_f32_e32 v101, v21
	v_exp_f32_e32 v102, v22
	v_exp_f32_e32 v103, v23
	v_exp_f32_e32 v104, v24
	v_exp_f32_e32 v105, v25
	v_exp_f32_e32 v106, v26
	v_exp_f32_e32 v107, v27
	v_exp_f32_e32 v108, v28
	v_exp_f32_e32 v109, v29
	v_exp_f32_e32 v110, v30
	v_exp_f32_e32 v111, v31
	v_exp_f32_e32 v112, v32
	v_exp_f32_e32 v113, v33
	v_exp_f32_e32 v84, v4
	v_exp_f32_e32 v85, v5
	v_exp_f32_e32 v86, v6
	v_exp_f32_e32 v87, v7
	v_exp_f32_e32 v88, v8
	v_exp_f32_e32 v89, v9
	v_exp_f32_e32 v90, v10
	v_exp_f32_e32 v91, v11
	v_exp_f32_e32 v92, v12
	v_exp_f32_e32 v93, v13
	v_exp_f32_e32 v94, v14
	v_exp_f32_e32 v95, v15
	v_exp_f32_e32 v96, v16
	v_exp_f32_e32 v97, v17
	v_lshl_or_b32 v235, v234, 8, v0
	v_add_u32_e32 v0, 0, v239
	s_waitcnt vmcnt(3) lgkmcnt(0)
	s_barrier
	v_add3_u32 v240, v0, v237, v235
	v_and_b32_e32 v0, 3, v222
	s_mov_b32 s10, 1
	s_mov_b32 s34, 0
	s_mov_b32 s4, 0
	s_cmp_lt_i32 s13, 7
	v_lshlrev_b32_e32 v0, 4, v0
	s_cbranch_scc1 .LBB0_1068
	v_readlane_b32 s30, v254, 10
	s_add_i32 s0, s13, -5
	v_readlane_b32 s31, v254, 11
	v_readlane_b32 s1, v254, 7
	v_mov_b32_e32 v66, 0
	v_lshl_add_u64 v[2:3], s[30:31], 0, v[212:213]
	s_add_u32 s30, s52, s1
	v_lshl_add_u64 v[2:3], v[2:3], 0, v[0:1]
	s_addc_u32 s31, s53, 0
	v_lshl_add_u64 v[214:215], s[54:55], 1, v[2:3]
	v_lshl_add_u64 v[216:217], s[30:31], 0, v[210:211]
	s_movk_i32 s18, 0x4000
	s_movk_i32 s12, 0x2000
	v_mov_b32_e32 v34, 0
	v_mov_b32_e32 v35, v66
	v_mov_b32_e32 v36, v66
	v_mov_b32_e32 v37, v66
	v_mov_b32_e32 v38, v66
	v_mov_b32_e32 v39, v66
	v_mov_b32_e32 v40, v66
	v_mov_b32_e32 v41, v66
	v_mov_b32_e32 v42, v66
	v_mov_b32_e32 v43, v66
	v_mov_b32_e32 v44, v66
	v_mov_b32_e32 v45, v66
	v_mov_b32_e32 v46, v66
	v_mov_b32_e32 v47, v66
	v_mov_b32_e32 v48, v66
	v_mov_b32_e32 v49, v66
	v_mov_b32_e32 v50, 0
	v_mov_b32_e32 v51, v66
	v_mov_b32_e32 v52, v66
	v_mov_b32_e32 v53, v66
	v_mov_b32_e32 v54, v66
	v_mov_b32_e32 v55, v66
	v_mov_b32_e32 v56, v66
	v_mov_b32_e32 v57, v66
	v_mov_b32_e32 v58, v66
	v_mov_b32_e32 v59, v66
	v_mov_b32_e32 v60, v66
	v_mov_b32_e32 v61, v66
	v_mov_b32_e32 v62, v66
	v_mov_b32_e32 v63, v66
	v_mov_b32_e32 v64, v66
	v_mov_b32_e32 v65, v66
	v_mov_b32_e32 v2, 0
	v_mov_b32_e32 v3, v66
	v_mov_b32_e32 v4, v66
	v_mov_b32_e32 v5, v66
	v_mov_b32_e32 v6, v66
	v_mov_b32_e32 v7, v66
	v_mov_b32_e32 v8, v66
	v_mov_b32_e32 v9, v66
	v_mov_b32_e32 v10, v66
	v_mov_b32_e32 v11, v66
	v_mov_b32_e32 v12, v66
	v_mov_b32_e32 v13, v66
	v_mov_b32_e32 v14, v66
	v_mov_b32_e32 v15, v66
	v_mov_b32_e32 v16, v66
	v_mov_b32_e32 v17, v66
	v_mov_b32_e32 v18, 0
	v_mov_b32_e32 v19, v66
	v_mov_b32_e32 v20, v66
	v_mov_b32_e32 v21, v66
	v_mov_b32_e32 v22, v66
	v_mov_b32_e32 v23, v66
	v_mov_b32_e32 v24, v66
	v_mov_b32_e32 v25, v66
	v_mov_b32_e32 v26, v66
	v_mov_b32_e32 v27, v66
	v_mov_b32_e32 v28, v66
	v_mov_b32_e32 v29, v66
	v_mov_b32_e32 v30, v66
	v_mov_b32_e32 v31, v66
	v_mov_b32_e32 v32, v66
	v_mov_b32_e32 v33, v66
	v_readlane_b32 s98, v254, 2
.LBB0_1062:
	s_mov_b32 s34, s18
	s_mov_b32 s1, s12
	v_lshl_add_u32 v218, s4, 1, v240
	ds_read_b64_tr_b16 v[68:69], v218 offset:24576
	ds_read_b64_tr_b16 v[70:71], v218 offset:25088
	v_add_f32_e32 v67, v98, v99
	v_add_f32_e32 v67, v100, v67
	v_add_f32_e32 v67, v101, v67
	v_add_f32_e32 v67, v102, v67
	v_add_f32_e32 v67, v103, v67
	v_cvt_pk_bf16_f32 v162, v98, v99
	v_cvt_pk_bf16_f32 v163, v100, v101
	s_waitcnt lgkmcnt(9)
	v_mfma_f32_32x32x16_bf16 v[130:145], v[206:209], v[174:177], 0
	ds_read_b64_tr_b16 v[72:73], v218 offset:28672
	ds_read_b64_tr_b16 v[74:75], v218 offset:29184
	v_add_f32_e32 v67, v104, v67
	v_add_f32_e32 v67, v105, v67
	v_add_f32_e32 v67, v106, v67
	v_add_f32_e32 v67, v107, v67
	v_cvt_pk_bf16_f32 v164, v102, v103
	v_cvt_pk_bf16_f32 v165, v104, v105
	s_waitcnt lgkmcnt(10)
	v_mfma_f32_32x32x16_bf16 v[114:129], v[202:205], v[174:177], 0
	ds_read_b64_tr_b16 v[76:77], v218 offset:25600
	ds_read_b64_tr_b16 v[78:79], v218 offset:26112
	v_add_f32_e32 v67, v108, v67
	v_add_f32_e32 v67, v109, v67
	v_add_f32_e32 v67, v110, v67
	v_add_f32_e32 v67, v111, v67
	v_cvt_pk_bf16_f32 v158, v106, v107
	v_cvt_pk_bf16_f32 v159, v108, v109
	s_waitcnt lgkmcnt(11)
	v_mfma_f32_32x32x16_bf16 v[130:145], v[198:201], v[170:173], v[130:145]
	ds_read_b64_tr_b16 v[98:99], v218 offset:29696
	ds_read_b64_tr_b16 v[100:101], v218 offset:30208
	v_add_f32_e32 v67, v112, v67
	v_add_f32_e32 v67, v113, v67
	v_add_f32_e32 v67, v82, v67
	v_add_f32_e32 v67, v83, v67
	v_cvt_pk_bf16_f32 v160, v110, v111
	v_cvt_pk_bf16_f32 v161, v112, v113
	s_waitcnt lgkmcnt(12)
	v_mfma_f32_32x32x16_bf16 v[114:129], v[194:197], v[170:173], v[114:129]
	ds_read_b64_tr_b16 v[102:103], v218 offset:26624
	ds_read_b64_tr_b16 v[104:105], v218 offset:27136
	v_add_f32_e32 v67, v84, v67
	v_add_f32_e32 v67, v85, v67
	v_add_f32_e32 v67, v86, v67
	v_add_f32_e32 v67, v87, v67
	v_cvt_pk_bf16_f32 v150, v82, v83
	v_cvt_pk_bf16_f32 v151, v84, v85
	s_waitcnt lgkmcnt(13)
	v_mfma_f32_32x32x16_bf16 v[130:145], v[190:193], v[166:169], v[130:145]
	ds_read_b64_tr_b16 v[106:107], v218 offset:30720
	ds_read_b64_tr_b16 v[108:109], v218 offset:31232
	v_add_f32_e32 v67, v88, v67
	v_add_f32_e32 v67, v89, v67
	v_add_f32_e32 v67, v90, v67
	v_add_f32_e32 v67, v91, v67
	v_cvt_pk_bf16_f32 v152, v86, v87
	v_cvt_pk_bf16_f32 v153, v88, v89
	s_waitcnt lgkmcnt(14)
	v_mfma_f32_32x32x16_bf16 v[114:129], v[186:189], v[166:169], v[114:129]
	ds_read_b64_tr_b16 v[110:111], v218 offset:27648
	ds_read_b64_tr_b16 v[112:113], v218 offset:28160
	v_add_f32_e32 v67, v92, v67
	v_add_f32_e32 v67, v93, v67
	v_add_f32_e32 v67, v94, v67
	v_add_f32_e32 v67, v95, v67
	v_cvt_pk_bf16_f32 v146, v90, v91
	v_cvt_pk_bf16_f32 v147, v92, v93
	s_waitcnt lgkmcnt(14)
	v_mfma_f32_32x32x16_bf16 v[130:145], v[182:185], v[154:157], v[130:145]
	ds_read_b64_tr_b16 v[90:91], v218 offset:31744
	ds_read_b64_tr_b16 v[92:93], v218 offset:32256
	v_add_f32_e32 v67, v96, v67
	v_add_f32_e32 v67, v97, v67
	v_add_f32_e32 v67, 0, v67
	v_cvt_pk_bf16_f32 v148, v94, v95
	v_cvt_pk_bf16_f32 v149, v96, v97
	v_mfma_f32_32x32x16_bf16 v[114:129], v[178:181], v[154:157], v[114:129]
	v_add_f32_e32 v198, v66, v67
	s_bitcmp1_b32 s98, 2
	s_cbranch_scc0 .Lstg_m1
	v_lshl_add_u64 v[188:189], s[8:9], 0, v[216:217]
	s_add_i32 s4, s12, s96
	v_lshl_add_u64 v[66:67], v[188:189], 0, s[22:23]
	s_mov_b32 s5, m0
	s_mov_b32 m0, s4
	s_nop 0
	global_load_lds_dwordx4 v[66:67], off
	s_mov_b32 m0, s5
	v_lshl_add_u64 v[186:187], s[8:9], 0, v[214:215]
	s_lshl_b32 s4, s18, 1
	v_lshl_add_u64 v[66:67], v[186:187], 0, s[24:25]
	s_add_i32 s4, s4, s79
	s_mov_b32 s5, m0
	s_mov_b32 m0, s4
	s_nop 0
	global_load_lds_dwordx4 v[66:67], off
	s_mov_b32 m0, s5
	v_lshl_add_u64 v[66:67], v[186:187], 0, s[26:27]
	s_addk_i32 s4, 0x2000
	s_mov_b32 s5, m0
	s_mov_b32 m0, s4
	s_nop 0
	global_load_lds_dwordx4 v[66:67], off
	s_mov_b32 m0, s5
	s_waitcnt vmcnt(3) lgkmcnt(0)
	s_barrier
.Lstg_m1:
	s_waitcnt lgkmcnt(14)
	v_mfma_f32_32x32x16_bf16 v[34:49], v[162:165], v[68:71], v[34:49]
	v_exp_f32_e32 v130, v130
	v_exp_f32_e32 v131, v131
	ds_read_b64_tr_b16 v[94:95], v218 offset:32768
	ds_read_b64_tr_b16 v[96:97], v218 offset:33280
	s_waitcnt lgkmcnt(14)
	v_mfma_f32_32x32x16_bf16 v[50:65], v[162:165], v[72:75], v[50:65]
	v_exp_f32_e32 v132, v132
	v_exp_f32_e32 v133, v133
	ds_read_b64_tr_b16 v[190:191], v218 offset:36864
	ds_read_b64_tr_b16 v[192:193], v218 offset:37376
	v_add_u32_e32 v66, s34, v238
	ds_read_b128 v[86:89], v66
	ds_read_b128 v[82:85], v66 offset:512
	s_waitcnt lgkmcnt(14)
	v_mfma_f32_32x32x16_bf16 v[34:49], v[158:161], v[76:79], v[34:49]
	v_exp_f32_e32 v134, v134
	v_exp_f32_e32 v135, v135
	ds_read_b64_tr_b16 v[194:195], v218 offset:33792
	ds_read_b64_tr_b16 v[196:197], v218 offset:34304
	ds_read_b128 v[182:185], v66 offset:2048
	ds_read_b128 v[78:81], v66 offset:2560
	v_mfma_f32_32x32x16_bf16 v[50:65], v[158:161], v[98:101], v[50:65]
	v_exp_f32_e32 v136, v136
	v_exp_f32_e32 v137, v137
	ds_read_b64_tr_b16 v[98:99], v218 offset:37888
	ds_read_b64_tr_b16 v[100:101], v218 offset:38400
	ds_read_b128 v[178:181], v66 offset:4096
	ds_read_b128 v[70:73], v66 offset:4608
	s_waitcnt lgkmcnt(14)
	v_mfma_f32_32x32x16_bf16 v[34:49], v[150:153], v[102:105], v[34:49]
	v_exp_f32_e32 v138, v138
	v_exp_f32_e32 v139, v139
	ds_read_b64_tr_b16 v[102:103], v218 offset:34816
	ds_read_b64_tr_b16 v[104:105], v218 offset:35328
	ds_read_b128 v[74:77], v66 offset:6144
	ds_read_b128 v[66:69], v66 offset:6656
	v_mfma_f32_32x32x16_bf16 v[50:65], v[150:153], v[106:109], v[50:65]
	v_exp_f32_e32 v140, v140
	v_exp_f32_e32 v141, v141
	ds_read_b64_tr_b16 v[106:107], v218 offset:38912
	ds_read_b64_tr_b16 v[108:109], v218 offset:39424
	v_mfma_f32_32x32x16_bf16 v[34:49], v[146:149], v[110:113], v[34:49]
	v_exp_f32_e32 v142, v142
	v_exp_f32_e32 v143, v143
	ds_read_b64_tr_b16 v[110:111], v218 offset:35840
	ds_read_b64_tr_b16 v[112:113], v218 offset:36352
	v_mfma_f32_32x32x16_bf16 v[50:65], v[146:149], v[90:93], v[50:65]
	v_exp_f32_e32 v144, v144
	v_exp_f32_e32 v145, v145
	ds_read_b64_tr_b16 v[90:91], v218 offset:39936
	ds_read_b64_tr_b16 v[92:93], v218 offset:40448
	s_waitcnt lgkmcnt(14)
	v_mfma_f32_32x32x16_bf16 v[2:17], v[162:165], v[94:97], v[2:17]
	v_exp_f32_e32 v114, v114
	v_exp_f32_e32 v115, v115
	v_mfma_f32_32x32x16_bf16 v[18:33], v[162:165], v[190:193], v[18:33]
	v_exp_f32_e32 v116, v116
	v_exp_f32_e32 v117, v117
	v_mfma_f32_32x32x16_bf16 v[2:17], v[158:161], v[194:197], v[2:17]
	v_exp_f32_e32 v118, v118
	v_exp_f32_e32 v119, v119
	s_waitcnt lgkmcnt(12)
	v_mfma_f32_32x32x16_bf16 v[18:33], v[158:161], v[98:101], v[18:33]
	v_exp_f32_e32 v120, v120
	v_exp_f32_e32 v121, v121
	s_waitcnt lgkmcnt(8)
	v_mfma_f32_32x32x16_bf16 v[2:17], v[150:153], v[102:105], v[2:17]
	v_exp_f32_e32 v122, v122
	v_exp_f32_e32 v123, v123
	s_waitcnt lgkmcnt(4)
	v_mfma_f32_32x32x16_bf16 v[18:33], v[150:153], v[106:109], v[18:33]
	v_exp_f32_e32 v124, v124
	v_exp_f32_e32 v125, v125
	s_waitcnt lgkmcnt(2)
	v_mfma_f32_32x32x16_bf16 v[2:17], v[146:149], v[110:113], v[2:17]
	v_exp_f32_e32 v126, v126
	v_exp_f32_e32 v127, v127
	s_waitcnt lgkmcnt(0)
	v_mfma_f32_32x32x16_bf16 v[18:33], v[146:149], v[90:93], v[18:33]
	v_exp_f32_e32 v128, v128
	v_exp_f32_e32 v129, v129
	s_waitcnt lgkmcnt(0)
	s_bitcmp1_b32 s98, 2
	s_cbranch_scc1 .Lstg_e1
	s_waitcnt vmcnt(0)
	s_barrier
	v_lshl_add_u64 v[252:253], s[8:9], 0, v[216:217]
	s_add_i32 s99, s12, s96
	v_lshl_add_u64 v[250:251], v[252:253], 0, s[22:23]
	s_mov_b32 s100, m0
	s_mov_b32 m0, s99
	s_nop 0
	global_load_lds_dwordx4 v[250:251], off
	v_lshl_add_u64 v[248:249], s[8:9], 0, v[214:215]
	s_lshl_b32 s99, s18, 1
	v_lshl_add_u64 v[250:251], v[248:249], 0, s[24:25]
	s_add_i32 s99, s99, s79
	s_mov_b32 m0, s99
	s_nop 0
	global_load_lds_dwordx4 v[250:251], off
	v_lshl_add_u64 v[250:251], v[248:249], 0, s[26:27]
	s_addk_i32 s99, 0x2000
	s_mov_b32 m0, s99
	s_nop 0
	global_load_lds_dwordx4 v[250:251], off
	s_mov_b32 m0, s100
.Lstg_e1:
	s_add_i32 s4, s18, 0x2000
	s_cmpk_lg_i32 s18, 0x4000
	s_cselect_b32 s12, s4, 0
	v_lshl_add_u32 v218, s1, 1, v240
	ds_read_b64_tr_b16 v[190:191], v218 offset:24576
	ds_read_b64_tr_b16 v[192:193], v218 offset:25088
	v_mfma_f32_32x32x16_bf16 v[98:113], v[86:89], v[174:177], 0
	v_add_f32_e32 v90, v130, v131
	v_add_f32_e32 v90, v132, v90
	v_add_f32_e32 v90, v133, v90
	v_add_f32_e32 v90, v134, v90
	v_add_f32_e32 v90, v135, v90
	v_cvt_pk_bf16_f32 v162, v130, v131
	v_cvt_pk_bf16_f32 v163, v132, v133
	ds_read_b64_tr_b16 v[130:131], v218 offset:28672
	ds_read_b64_tr_b16 v[132:133], v218 offset:29184
	v_add_f32_e32 v86, v136, v90
	v_add_f32_e32 v86, v137, v86
	v_add_f32_e32 v86, v138, v86
	v_add_f32_e32 v146, v139, v86
	v_mfma_f32_32x32x16_bf16 v[82:97], v[82:85], v[174:177], 0
	v_cvt_pk_bf16_f32 v164, v134, v135
	v_cvt_pk_bf16_f32 v165, v136, v137
	ds_read_b64_tr_b16 v[134:135], v218 offset:25600
	ds_read_b64_tr_b16 v[136:137], v218 offset:26112
	v_mfma_f32_32x32x16_bf16 v[98:113], v[182:185], v[170:173], v[98:113]
	v_add_f32_e32 v146, v140, v146
	v_add_f32_e32 v146, v141, v146
	v_add_f32_e32 v146, v142, v146
	v_add_f32_e32 v146, v143, v146
	v_cvt_pk_bf16_f32 v158, v138, v139
	v_cvt_pk_bf16_f32 v159, v140, v141
	ds_read_b64_tr_b16 v[138:139], v218 offset:29696
	ds_read_b64_tr_b16 v[140:141], v218 offset:30208
	v_mfma_f32_32x32x16_bf16 v[82:97], v[78:81], v[170:173], v[82:97]
	v_add_f32_e32 v146, v144, v146
	v_add_f32_e32 v146, v145, v146
	v_add_f32_e32 v146, v114, v146
	v_add_f32_e32 v146, v115, v146
	v_cvt_pk_bf16_f32 v160, v142, v143
	v_cvt_pk_bf16_f32 v161, v144, v145
	ds_read_b64_tr_b16 v[78:79], v218 offset:26624
	ds_read_b64_tr_b16 v[80:81], v218 offset:27136
	v_mfma_f32_32x32x16_bf16 v[98:113], v[178:181], v[166:169], v[98:113]
	v_add_f32_e32 v142, v116, v146
	v_add_f32_e32 v142, v117, v142
	v_add_f32_e32 v142, v118, v142
	v_add_f32_e32 v142, v119, v142
	v_cvt_pk_bf16_f32 v150, v114, v115
	v_cvt_pk_bf16_f32 v151, v116, v117
	ds_read_b64_tr_b16 v[114:115], v218 offset:30720
	ds_read_b64_tr_b16 v[116:117], v218 offset:31232
	v_mfma_f32_32x32x16_bf16 v[82:97], v[70:73], v[166:169], v[82:97]
	v_add_f32_e32 v142, v120, v142
	v_add_f32_e32 v142, v121, v142
	v_add_f32_e32 v142, v122, v142
	v_add_f32_e32 v142, v123, v142
	v_cvt_pk_bf16_f32 v152, v118, v119
	v_cvt_pk_bf16_f32 v153, v120, v121
	ds_read_b64_tr_b16 v[70:71], v218 offset:27648
	ds_read_b64_tr_b16 v[72:73], v218 offset:28160
	v_mfma_f32_32x32x16_bf16 v[98:113], v[74:77], v[154:157], v[98:113]
	v_add_f32_e32 v118, v124, v142
	v_add_f32_e32 v118, v125, v118
	v_add_f32_e32 v118, v126, v118
	v_add_f32_e32 v118, v127, v118
	v_cvt_pk_bf16_f32 v146, v122, v123
	v_cvt_pk_bf16_f32 v147, v124, v125
	ds_read_b64_tr_b16 v[74:75], v218 offset:31744
	ds_read_b64_tr_b16 v[76:77], v218 offset:32256
	v_mfma_f32_32x32x16_bf16 v[82:97], v[66:69], v[154:157], v[82:97]
	v_add_f32_e32 v118, v128, v118
	v_add_f32_e32 v118, v129, v118
	v_add_f32_e32 v118, 0, v118
	v_cvt_pk_bf16_f32 v148, v126, v127
	v_cvt_pk_bf16_f32 v149, v128, v129
	s_bitcmp1_b32 s98, 2
	s_cbranch_scc0 .Lstg_m2
	s_add_i32 s1, s18, s96
	v_lshl_add_u64 v[68:69], v[188:189], 0, s[28:29]
	s_mov_b32 s4, m0
	s_mov_b32 m0, s1
	s_nop 0
	global_load_lds_dwordx4 v[68:69], off
	s_mov_b32 m0, s4
	s_lshl_b32 s1, s12, 1
	v_lshl_add_u64 v[68:69], v[186:187], 0, s[38:39]
	s_add_i32 s1, s1, s79
	s_mov_b32 s4, m0
	s_mov_b32 m0, s1
	s_nop 0
	global_load_lds_dwordx4 v[68:69], off
	s_mov_b32 m0, s4
	v_lshl_add_u64 v[68:69], v[186:187], 0, s[40:41]
	s_addk_i32 s1, 0x2000
	s_mov_b32 s4, m0
	s_mov_b32 m0, s1
	s_nop 0
	global_load_lds_dwordx4 v[68:69], off
	s_mov_b32 m0, s4
	s_waitcnt vmcnt(3) lgkmcnt(0)
	s_barrier
; #define WAIT_BAR(N) asm volatile("s_waitcnt vmcnt(" #N ") lgkmcnt(0)\n\ts_barrier":::"memory")
;   #define RESC() do{ if constexpr(!FIXED) if(resc){ asm volatile("s_waitcnt lgkmcnt(0)":::"memory"); \
;       _Pragma("unroll") for(int d_=0;d_<4;++d_) _Pragma("unroll") for(int r=0;r<16;++r)o[d_][r]*=wsf[crow(r,hi)]; } }while(0)
;   #define ROT() do{sl_prev=sl_cur;sl_cur=sl_next;sl_next=(sl_next==(NSLOT-1)*SLOTB)?0:sl_next+SLOTB;}while(0)
; template<int THRL,bool FIXED> __device__ __forceinline__ void attn_unit(int qb,const bf16*Q,const bf16*__restrict__ Kh,const bf16*__restrict__ Vh,bf16*O,const int*__restrict__ cid,char*shm,const int wid){
;     ...
;   int t=1;
;     ...
;   for(;t+5<NT;t+=2){
;     STEP(pB0,pB1,pA0,pA1,t,true,true,true);     WAIT_BAR(3); RESC(); ROT();
;     STEP(pA0,pA1,pB0,pB1,t+1,true,true,true);   WAIT_BAR(3); RESC(); ROT();
;   }
.Lstg_m2:
	v_add_f32_e32 v66, v198, v118
	s_add_i32 s10, s10, 2
	s_waitcnt lgkmcnt(14)
	v_mfma_f32_32x32x16_bf16 v[34:49], v[162:165], v[190:193], v[34:49]
	v_exp_f32_e32 v98, v98
	v_exp_f32_e32 v99, v99
	ds_read_b64_tr_b16 v[118:119], v218 offset:32768
	ds_read_b64_tr_b16 v[120:121], v218 offset:33280
	s_waitcnt lgkmcnt(14)
	v_mfma_f32_32x32x16_bf16 v[50:65], v[162:165], v[130:133], v[50:65]
	v_exp_f32_e32 v100, v100
	v_exp_f32_e32 v101, v101
	ds_read_b64_tr_b16 v[122:123], v218 offset:36864
	ds_read_b64_tr_b16 v[124:125], v218 offset:37376
	v_add_u32_e32 v67, s12, v238
	ds_read_b128 v[206:209], v67
	ds_read_b128 v[202:205], v67 offset:512
	s_waitcnt lgkmcnt(14)
	v_mfma_f32_32x32x16_bf16 v[34:49], v[158:161], v[134:137], v[34:49]
	v_exp_f32_e32 v102, v102
	v_exp_f32_e32 v103, v103
	ds_read_b64_tr_b16 v[126:127], v218 offset:33792
	ds_read_b64_tr_b16 v[128:129], v218 offset:34304
	ds_read_b128 v[198:201], v67 offset:2048
	ds_read_b128 v[194:197], v67 offset:2560
	v_mfma_f32_32x32x16_bf16 v[50:65], v[158:161], v[138:141], v[50:65]
	v_exp_f32_e32 v104, v104
	v_exp_f32_e32 v105, v105
	ds_read_b64_tr_b16 v[130:131], v218 offset:37888
	ds_read_b64_tr_b16 v[132:133], v218 offset:38400
	ds_read_b128 v[190:193], v67 offset:4096
	ds_read_b128 v[186:189], v67 offset:4608
	s_waitcnt lgkmcnt(14)
	v_mfma_f32_32x32x16_bf16 v[34:49], v[150:153], v[78:81], v[34:49]
	v_exp_f32_e32 v106, v106
	v_exp_f32_e32 v107, v107
	ds_read_b64_tr_b16 v[78:79], v218 offset:34816
	ds_read_b64_tr_b16 v[80:81], v218 offset:35328
	ds_read_b128 v[182:185], v67 offset:6144
	ds_read_b128 v[178:181], v67 offset:6656
	v_mfma_f32_32x32x16_bf16 v[50:65], v[150:153], v[114:117], v[50:65]
	v_exp_f32_e32 v108, v108
	v_exp_f32_e32 v109, v109
	ds_read_b64_tr_b16 v[114:115], v218 offset:38912
	ds_read_b64_tr_b16 v[116:117], v218 offset:39424
	v_mfma_f32_32x32x16_bf16 v[34:49], v[146:149], v[70:73], v[34:49]
	v_exp_f32_e32 v110, v110
	v_exp_f32_e32 v111, v111
	ds_read_b64_tr_b16 v[68:69], v218 offset:35840
	ds_read_b64_tr_b16 v[70:71], v218 offset:36352
	v_mfma_f32_32x32x16_bf16 v[50:65], v[146:149], v[74:77], v[50:65]
	v_exp_f32_e32 v112, v112
	v_exp_f32_e32 v113, v113
	ds_read_b64_tr_b16 v[72:73], v218 offset:39936
	ds_read_b64_tr_b16 v[74:75], v218 offset:40448
	s_waitcnt lgkmcnt(14)
	v_mfma_f32_32x32x16_bf16 v[2:17], v[162:165], v[118:121], v[2:17]
	v_exp_f32_e32 v82, v82
	v_exp_f32_e32 v83, v83
	v_mfma_f32_32x32x16_bf16 v[18:33], v[162:165], v[122:125], v[18:33]
	v_exp_f32_e32 v84, v84
	v_exp_f32_e32 v85, v85
	v_mfma_f32_32x32x16_bf16 v[2:17], v[158:161], v[126:129], v[2:17]
	v_exp_f32_e32 v86, v86
	v_exp_f32_e32 v87, v87
	s_waitcnt lgkmcnt(12)
	v_mfma_f32_32x32x16_bf16 v[18:33], v[158:161], v[130:133], v[18:33]
	v_exp_f32_e32 v88, v88
	v_exp_f32_e32 v89, v89
	s_waitcnt lgkmcnt(8)
	v_mfma_f32_32x32x16_bf16 v[2:17], v[150:153], v[78:81], v[2:17]
	v_exp_f32_e32 v90, v90
	v_exp_f32_e32 v91, v91
	s_waitcnt lgkmcnt(4)
	v_mfma_f32_32x32x16_bf16 v[18:33], v[150:153], v[114:117], v[18:33]
	v_exp_f32_e32 v92, v92
	v_exp_f32_e32 v93, v93
	s_waitcnt lgkmcnt(2)
	v_mfma_f32_32x32x16_bf16 v[2:17], v[146:149], v[68:71], v[2:17]
	v_exp_f32_e32 v94, v94
	v_exp_f32_e32 v95, v95
	s_waitcnt lgkmcnt(0)
	v_mfma_f32_32x32x16_bf16 v[18:33], v[146:149], v[72:75], v[18:33]
	v_exp_f32_e32 v96, v96
	v_exp_f32_e32 v97, v97
	s_waitcnt lgkmcnt(0)
	s_bitcmp1_b32 s98, 2
	s_cbranch_scc1 .Lstg_e2
	s_waitcnt vmcnt(0)
	s_barrier
	s_add_i32 s99, s18, s96
	v_lshl_add_u64 v[250:251], v[252:253], 0, s[28:29]
	s_mov_b32 s100, m0
	s_mov_b32 m0, s99
	s_nop 0
	global_load_lds_dwordx4 v[250:251], off
	s_lshl_b32 s99, s12, 1
	v_lshl_add_u64 v[250:251], v[248:249], 0, s[38:39]
	s_add_i32 s99, s99, s79
	s_mov_b32 m0, s99
	s_nop 0
	global_load_lds_dwordx4 v[250:251], off
	v_lshl_add_u64 v[250:251], v[248:249], 0, s[40:41]
	s_addk_i32 s99, 0x2000
	s_mov_b32 m0, s99
	s_nop 0
	global_load_lds_dwordx4 v[250:251], off
	s_mov_b32 m0, s100
.Lstg_e2:
	s_add_i32 s1, s12, 0x2000
	s_cmpk_lg_i32 s12, 0x4000
	s_cselect_b32 s18, s1, 0
	v_lshl_add_u64 v[214:215], v[214:215], 0, s[16:17]
	v_lshl_add_u64 v[216:217], v[216:217], 0, s[16:17]
	s_cmp_ge_i32 s10, s0
	s_mov_b32 s4, s34
	s_cbranch_scc0 .LBB0_1062
	s_waitcnt lgkmcnt(0)
	s_barrier
	s_add_i32 s0, s10, 1
	s_cmp_lt_i32 s0, s13
	v_lshlrev_b32_e32 v67, 4, v234
	s_cbranch_scc1 .LBB0_1069

; __global__ void __launch_bounds__(NTHR, 2) mk_fwd(Args args) {
	.amdhsa_kernel _Z6mk_fwd4Args
		.amdhsa_group_segment_fixed_size 0
		.amdhsa_private_segment_fixed_size 0
		.amdhsa_kernarg_size 552
		.amdhsa_user_sgpr_count 2
		.amdhsa_user_sgpr_dispatch_ptr 0
		.amdhsa_user_sgpr_queue_ptr 0
		.amdhsa_user_sgpr_kernarg_segment_ptr 1
		.amdhsa_user_sgpr_dispatch_id 0
		.amdhsa_user_sgpr_kernarg_preload_length 0
		.amdhsa_user_sgpr_kernarg_preload_offset 0
		.amdhsa_user_sgpr_private_segment_size 0
		.amdhsa_uses_dynamic_stack 0
		.amdhsa_enable_private_segment 0
		.amdhsa_system_sgpr_workgroup_id_x 1
		.amdhsa_system_sgpr_workgroup_id_y 0
		.amdhsa_system_sgpr_workgroup_id_z 0
		.amdhsa_system_sgpr_workgroup_info 0
		.amdhsa_system_vgpr_workitem_id 2
		.amdhsa_next_free_vgpr 255
		.amdhsa_next_free_sgpr 102
		.amdhsa_accum_offset 256
		.amdhsa_reserve_vcc 1
		.amdhsa_float_round_mode_32 0
		.amdhsa_float_round_mode_16_64 0
		.amdhsa_float_denorm_mode_32 3
		.amdhsa_float_denorm_mode_16_64 3
		.amdhsa_dx10_clamp 1
		.amdhsa_ieee_mode 1
		.amdhsa_fp16_overflow 0
		.amdhsa_tg_split 0
		.amdhsa_exception_fp_ieee_invalid_op 0
		.amdhsa_exception_fp_denorm_src 0
		.amdhsa_exception_fp_ieee_div_zero 0
		.amdhsa_exception_fp_ieee_overflow 0
		.amdhsa_exception_fp_ieee_underflow 0
		.amdhsa_exception_fp_ieee_inexact 0
		.amdhsa_exception_int_div_zero 0
	.end_amdhsa_kernel

; __global__ void __launch_bounds__(NTHR, 2) mk_fwd(Args args) {
amdhsa.kernels:
  - .agpr_count:     0
    .args:
      - .offset:         0
        .size:           296
        .value_kind:     by_value
      - .offset:         296
        .size:           4
        .value_kind:     hidden_block_count_x
      - .offset:         300
        .size:           4
        .value_kind:     hidden_block_count_y
      - .offset:         304
        .size:           4
        .value_kind:     hidden_block_count_z
      - .offset:         308
        .size:           2
        .value_kind:     hidden_group_size_x
      - .offset:         310
        .size:           2
        .value_kind:     hidden_group_size_y
      - .offset:         312
        .size:           2
        .value_kind:     hidden_group_size_z
      - .offset:         314
        .size:           2
        .value_kind:     hidden_remainder_x
      - .offset:         316
        .size:           2
        .value_kind:     hidden_remainder_y
      - .offset:         318
        .size:           2
        .value_kind:     hidden_remainder_z
      - .offset:         336
        .size:           8
        .value_kind:     hidden_global_offset_x
      - .offset:         344
        .size:           8
        .value_kind:     hidden_global_offset_y
      - .offset:         352
        .size:           8
        .value_kind:     hidden_global_offset_z
      - .offset:         360
        .size:           2
        .value_kind:     hidden_grid_dims
      - .offset:         384
        .size:           8
        .value_kind:     hidden_multigrid_sync_arg
      - .offset:         416
        .size:           4
        .value_kind:     hidden_dynamic_lds_size
    .group_segment_fixed_size: 0
    .kernarg_segment_align: 8
    .kernarg_segment_size: 552
    .language:       OpenCL C
    .language_version:
      - 2
      - 0
    .max_flat_workgroup_size: 512
    .name:           _Z6mk_fwd4Args
    .private_segment_fixed_size: 0
    .sgpr_count:     108
    .sgpr_spill_count: 17
    .symbol:         _Z6mk_fwd4Args.kd
    .uniform_work_group_size: 1
    .uses_dynamic_stack: false
    .vgpr_count:     255
    .vgpr_spill_count: 0
    .wavefront_size: 64
